# cv46 + G1/G5 K-loops: LDS-DMA issue rebalanced from 2/6/2/6 to 4/4/4/4 pieces per load segment in scalar-base form (counted waits 8/6/8/6)
# baseline (speedup 1.0000x reference)
.LBB0_306:
	s_add_u32 s38, s36, 0xfff80080
	s_addc_u32 s39, s37, -1
	s_add_i32 s45, 0, 0x10000
	s_cmp_eq_u32 s27, 28
	s_cselect_b32 s43, s9, s39
	s_cselect_b32 s42, s14, s38
	v_add_u32_e32 v34, s45, v170
	s_cselect_b32 s39, s16, s26
	s_cselect_b32 s38, s17, s25
	s_add_i32 s47, 0, 0x14000
	ds_read_b128 v[160:163], v34
	ds_read_b128 v[164:167], v34 offset:1024
	ds_read_b128 v[174:177], v34 offset:2048
	ds_read_b128 v[184:187], v34 offset:3072
	v_add_u32_e32 v34, s47, v170
	ds_read_b128 v[188:191], v34
	ds_read_b128 v[192:195], v34 offset:1024
	ds_read_b128 v[196:199], v34 offset:2048
	ds_read_b128 v[200:203], v34 offset:3072
	s_cmp_lg_u32 s27, -2
	s_cbranch_scc0 .Lq306_nf
	s_mov_b32 m0, s61
	s_nop 0
	global_load_lds_dwordx4 v14, s[100:101]
	s_mov_b32 m0, s64
	s_nop 0
	global_load_lds_dwordx4 v138, s[100:101]
.Lq306_nf:
	s_add_i32 m0, s35, 0xc000
	ds_read_b128 v[214:217], v173
	ds_read_b128 v[218:221], v173 offset:1024
	ds_read_b128 v[222:225], v173 offset:2048
	ds_read_b128 v[226:229], v173 offset:3072
	ds_read_b128 v[230:233], v173 offset:4096
	ds_read_b128 v[234:237], v173 offset:5120
	ds_read_b128 v[238:241], v173 offset:6144
	ds_read_b128 v[242:245], v173 offset:7168
	global_load_lds_dwordx4 v152, s[36:37]
	s_add_i32 m0, s35, 0xe000
	s_nop 0
	global_load_lds_dwordx4 v156, s[36:37]
	s_waitcnt vmcnt(8)
	s_waitcnt lgkmcnt(0)
	s_barrier
	s_setprio 1
	s_waitcnt lgkmcnt(0)
	v_mfma_f32_16x16x32_bf16 v[132:135], v[160:163], v[214:217], v[132:135]
	v_mfma_f32_16x16x32_bf16 v[128:131], v[174:177], v[214:217], v[128:131]
	v_mfma_f32_16x16x32_bf16 v[116:119], v[160:163], v[222:225], v[116:119]
	v_mfma_f32_16x16x32_bf16 v[112:115], v[174:177], v[222:225], v[112:115]
	v_mfma_f32_16x16x32_bf16 v[100:103], v[160:163], v[230:233], v[100:103]
	v_mfma_f32_16x16x32_bf16 v[96:99], v[174:177], v[230:233], v[96:99]
	v_mfma_f32_16x16x32_bf16 v[84:87], v[160:163], v[238:241], v[84:87]
	v_mfma_f32_16x16x32_bf16 v[80:83], v[174:177], v[238:241], v[80:83]
	v_mfma_f32_16x16x32_bf16 v[132:135], v[164:167], v[218:221], v[132:135]
	v_mfma_f32_16x16x32_bf16 v[128:131], v[184:187], v[218:221], v[128:131]
	v_mfma_f32_16x16x32_bf16 v[116:119], v[164:167], v[226:229], v[116:119]
	v_mfma_f32_16x16x32_bf16 v[112:115], v[184:187], v[226:229], v[112:115]
	v_mfma_f32_16x16x32_bf16 v[100:103], v[164:167], v[234:237], v[100:103]
	v_mfma_f32_16x16x32_bf16 v[96:99], v[184:187], v[234:237], v[96:99]
	v_mfma_f32_16x16x32_bf16 v[84:87], v[164:167], v[242:245], v[84:87]
	v_mfma_f32_16x16x32_bf16 v[80:83], v[184:187], v[242:245], v[80:83]
	s_setprio 0
	s_setprio 1
	v_mfma_f32_16x16x32_bf16 v[124:127], v[188:191], v[214:217], v[124:127]
	v_mfma_f32_16x16x32_bf16 v[120:123], v[196:199], v[214:217], v[120:123]
	v_mfma_f32_16x16x32_bf16 v[108:111], v[188:191], v[222:225], v[108:111]
	v_mfma_f32_16x16x32_bf16 v[104:107], v[196:199], v[222:225], v[104:107]
	v_mfma_f32_16x16x32_bf16 v[92:95], v[188:191], v[230:233], v[92:95]
	v_mfma_f32_16x16x32_bf16 v[88:91], v[196:199], v[230:233], v[88:91]
	v_mfma_f32_16x16x32_bf16 v[76:79], v[188:191], v[238:241], v[76:79]
	v_mfma_f32_16x16x32_bf16 v[72:75], v[196:199], v[238:241], v[72:75]
	v_mfma_f32_16x16x32_bf16 v[124:127], v[192:195], v[218:221], v[124:127]
	v_mfma_f32_16x16x32_bf16 v[120:123], v[200:203], v[218:221], v[120:123]
	v_mfma_f32_16x16x32_bf16 v[108:111], v[192:195], v[226:229], v[108:111]
	v_mfma_f32_16x16x32_bf16 v[104:107], v[200:203], v[226:229], v[104:107]
	v_mfma_f32_16x16x32_bf16 v[92:95], v[192:195], v[234:237], v[92:95]
	v_mfma_f32_16x16x32_bf16 v[88:91], v[200:203], v[234:237], v[88:91]
	v_mfma_f32_16x16x32_bf16 v[76:79], v[192:195], v[242:245], v[76:79]
	v_mfma_f32_16x16x32_bf16 v[72:75], v[200:203], v[242:245], v[72:75]
	s_setprio 0
	s_barrier
	s_add_u32 s98, s38, s22
	s_addc_u32 s99, s39, s23
	s_add_u32 s100, s42, s22
	s_addc_u32 s101, s43, s23
	s_add_i32 s45, s45, s53
	s_mov_b32 m0, s45
	ds_read_b128 v[214:217], v173 offset:16384
	ds_read_b128 v[218:221], v173 offset:17408
	ds_read_b128 v[222:225], v173 offset:18432
	ds_read_b128 v[226:229], v173 offset:19456
	ds_read_b128 v[230:233], v173 offset:20480
	ds_read_b128 v[234:237], v173 offset:21504
	ds_read_b128 v[238:241], v173 offset:22528
	ds_read_b128 v[242:245], v173 offset:23552
	global_load_lds_dwordx4 v136, s[38:39]
	s_add_i32 m0, s45, 0x2000
	s_add_u32 s70, s38, 0x80000
	s_addc_u32 s71, s39, 0
	s_add_i32 s45, s47, s53
	global_load_lds_dwordx4 v140, s[38:39]
	s_mov_b32 m0, s45
	s_nop 0
	global_load_lds_dwordx4 v136, s[70:71]
	s_add_i32 m0, s45, 0x2000
	s_nop 0
	global_load_lds_dwordx4 v140, s[70:71]
	s_waitcnt vmcnt(6)
	s_waitcnt lgkmcnt(0)
	s_barrier
	s_setprio 1
	s_waitcnt lgkmcnt(0)
	v_mfma_f32_16x16x32_bf16 v[68:71], v[160:163], v[214:217], v[68:71]
	v_mfma_f32_16x16x32_bf16 v[64:67], v[174:177], v[214:217], v[64:67]
	v_mfma_f32_16x16x32_bf16 v[52:55], v[160:163], v[222:225], v[52:55]
	v_mfma_f32_16x16x32_bf16 v[48:51], v[174:177], v[222:225], v[48:51]
	v_mfma_f32_16x16x32_bf16 v[36:39], v[160:163], v[230:233], v[36:39]
	v_mfma_f32_16x16x32_bf16 v[30:33], v[174:177], v[230:233], v[30:33]
	v_mfma_f32_16x16x32_bf16 v[18:21], v[160:163], v[238:241], v[18:21]
	v_mfma_f32_16x16x32_bf16 v[10:13], v[174:177], v[238:241], v[10:13]
	v_mfma_f32_16x16x32_bf16 v[68:71], v[164:167], v[218:221], v[68:71]
	v_mfma_f32_16x16x32_bf16 v[64:67], v[184:187], v[218:221], v[64:67]
	v_mfma_f32_16x16x32_bf16 v[52:55], v[164:167], v[226:229], v[52:55]
	v_mfma_f32_16x16x32_bf16 v[48:51], v[184:187], v[226:229], v[48:51]
	v_mfma_f32_16x16x32_bf16 v[36:39], v[164:167], v[234:237], v[36:39]
	v_mfma_f32_16x16x32_bf16 v[30:33], v[184:187], v[234:237], v[30:33]
	v_mfma_f32_16x16x32_bf16 v[18:21], v[164:167], v[242:245], v[18:21]
	v_mfma_f32_16x16x32_bf16 v[10:13], v[184:187], v[242:245], v[10:13]
	s_setprio 0
	s_setprio 1
	v_mfma_f32_16x16x32_bf16 v[60:63], v[188:191], v[214:217], v[60:63]
	v_mfma_f32_16x16x32_bf16 v[56:59], v[196:199], v[214:217], v[56:59]
	v_mfma_f32_16x16x32_bf16 v[44:47], v[188:191], v[222:225], v[44:47]
	v_mfma_f32_16x16x32_bf16 v[40:43], v[196:199], v[222:225], v[40:43]
	v_mfma_f32_16x16x32_bf16 v[26:29], v[188:191], v[230:233], v[26:29]
	v_mfma_f32_16x16x32_bf16 v[22:25], v[196:199], v[230:233], v[22:25]
	v_mfma_f32_16x16x32_bf16 v[6:9], v[188:191], v[238:241], v[6:9]
	v_mfma_f32_16x16x32_bf16 v[2:5], v[196:199], v[238:241], v[2:5]
	v_mfma_f32_16x16x32_bf16 v[60:63], v[192:195], v[218:221], v[60:63]
	v_mfma_f32_16x16x32_bf16 v[56:59], v[200:203], v[218:221], v[56:59]
	v_mfma_f32_16x16x32_bf16 v[44:47], v[192:195], v[226:229], v[44:47]
	v_mfma_f32_16x16x32_bf16 v[40:43], v[200:203], v[226:229], v[40:43]
	v_mfma_f32_16x16x32_bf16 v[26:29], v[192:195], v[234:237], v[26:29]
	v_mfma_f32_16x16x32_bf16 v[22:25], v[200:203], v[234:237], v[22:25]
	v_mfma_f32_16x16x32_bf16 v[6:9], v[192:195], v[242:245], v[6:9]
	v_mfma_f32_16x16x32_bf16 v[2:5], v[200:203], v[242:245], v[2:5]
	s_setprio 0
	s_barrier
	s_mov_b32 m0, s35
	s_nop 0
	global_load_lds_dwordx4 v14, s[42:43]
	s_mov_b32 m0, s54
	s_nop 0
	global_load_lds_dwordx4 v138, s[42:43]
	s_add_i32 s45, 0, 0x18000
	v_add_u32_e32 v34, s45, v170
	s_add_i32 s47, 0, 0x1c000
	ds_read_b128 v[160:163], v34
	ds_read_b128 v[164:167], v34 offset:1024
	ds_read_b128 v[174:177], v34 offset:2048
	ds_read_b128 v[184:187], v34 offset:3072
	v_add_u32_e32 v34, s47, v170
	ds_read_b128 v[188:191], v34
	ds_read_b128 v[192:195], v34 offset:1024
	ds_read_b128 v[196:199], v34 offset:2048
	ds_read_b128 v[200:203], v34 offset:3072
	s_add_u32 s42, s42, 0x80000
	s_addc_u32 s43, s43, 0
	s_mov_b32 m0, s55
	ds_read_b128 v[214:217], v173 offset:32768
	ds_read_b128 v[218:221], v173 offset:33792
	ds_read_b128 v[222:225], v173 offset:34816
	ds_read_b128 v[226:229], v173 offset:35840
	ds_read_b128 v[230:233], v173 offset:36864
	ds_read_b128 v[234:237], v173 offset:37888
	ds_read_b128 v[238:241], v173 offset:38912
	ds_read_b128 v[242:245], v173 offset:39936
	global_load_lds_dwordx4 v14, s[42:43]
	s_mov_b32 m0, s60
	s_nop 0
	global_load_lds_dwordx4 v138, s[42:43]
	s_waitcnt vmcnt(8)
	s_waitcnt lgkmcnt(0)
	s_barrier
	s_setprio 1
	s_waitcnt lgkmcnt(0)
	v_mfma_f32_16x16x32_bf16 v[132:135], v[160:163], v[214:217], v[132:135]
	v_mfma_f32_16x16x32_bf16 v[128:131], v[174:177], v[214:217], v[128:131]
	v_mfma_f32_16x16x32_bf16 v[116:119], v[160:163], v[222:225], v[116:119]
	v_mfma_f32_16x16x32_bf16 v[112:115], v[174:177], v[222:225], v[112:115]
	v_mfma_f32_16x16x32_bf16 v[100:103], v[160:163], v[230:233], v[100:103]
	v_mfma_f32_16x16x32_bf16 v[96:99], v[174:177], v[230:233], v[96:99]
	v_mfma_f32_16x16x32_bf16 v[84:87], v[160:163], v[238:241], v[84:87]
	v_mfma_f32_16x16x32_bf16 v[80:83], v[174:177], v[238:241], v[80:83]
	v_mfma_f32_16x16x32_bf16 v[132:135], v[164:167], v[218:221], v[132:135]
	v_mfma_f32_16x16x32_bf16 v[128:131], v[184:187], v[218:221], v[128:131]
	v_mfma_f32_16x16x32_bf16 v[116:119], v[164:167], v[226:229], v[116:119]
	v_mfma_f32_16x16x32_bf16 v[112:115], v[184:187], v[226:229], v[112:115]
	v_mfma_f32_16x16x32_bf16 v[100:103], v[164:167], v[234:237], v[100:103]
	v_mfma_f32_16x16x32_bf16 v[96:99], v[184:187], v[234:237], v[96:99]
	v_mfma_f32_16x16x32_bf16 v[84:87], v[164:167], v[242:245], v[84:87]
	v_mfma_f32_16x16x32_bf16 v[80:83], v[184:187], v[242:245], v[80:83]
	s_setprio 0
	s_setprio 1
	v_mfma_f32_16x16x32_bf16 v[124:127], v[188:191], v[214:217], v[124:127]
	v_mfma_f32_16x16x32_bf16 v[120:123], v[196:199], v[214:217], v[120:123]
	v_mfma_f32_16x16x32_bf16 v[108:111], v[188:191], v[222:225], v[108:111]
	v_mfma_f32_16x16x32_bf16 v[104:107], v[196:199], v[222:225], v[104:107]
	v_mfma_f32_16x16x32_bf16 v[92:95], v[188:191], v[230:233], v[92:95]
	v_mfma_f32_16x16x32_bf16 v[88:91], v[196:199], v[230:233], v[88:91]
	v_mfma_f32_16x16x32_bf16 v[76:79], v[188:191], v[238:241], v[76:79]
	v_mfma_f32_16x16x32_bf16 v[72:75], v[196:199], v[238:241], v[72:75]
	v_mfma_f32_16x16x32_bf16 v[124:127], v[192:195], v[218:221], v[124:127]
	v_mfma_f32_16x16x32_bf16 v[120:123], v[200:203], v[218:221], v[120:123]
	v_mfma_f32_16x16x32_bf16 v[108:111], v[192:195], v[226:229], v[108:111]
	v_mfma_f32_16x16x32_bf16 v[104:107], v[200:203], v[226:229], v[104:107]
	v_mfma_f32_16x16x32_bf16 v[92:95], v[192:195], v[234:237], v[92:95]
	v_mfma_f32_16x16x32_bf16 v[88:91], v[200:203], v[234:237], v[88:91]
	v_mfma_f32_16x16x32_bf16 v[76:79], v[192:195], v[242:245], v[76:79]
	v_mfma_f32_16x16x32_bf16 v[72:75], v[200:203], v[242:245], v[72:75]
	s_setprio 0
	s_barrier
	s_add_i32 s42, s45, s53
	s_mov_b32 m0, s42
	ds_read_b128 v[214:217], v173 offset:49152
	ds_read_b128 v[218:221], v173 offset:50176
	ds_read_b128 v[222:225], v173 offset:51200
	ds_read_b128 v[226:229], v173 offset:52224
	ds_read_b128 v[230:233], v173 offset:53248
	ds_read_b128 v[234:237], v173 offset:54272
	ds_read_b128 v[238:241], v173 offset:55296
	ds_read_b128 v[242:245], v173 offset:56320
	global_load_lds_dwordx4 v136, s[98:99]
	s_add_i32 m0, s42, 0x2000
	s_add_u32 s38, s38, 0x80080
	s_addc_u32 s39, s39, 0
	s_add_i32 s42, s47, s53
	global_load_lds_dwordx4 v140, s[98:99]
	s_mov_b32 m0, s42
	s_nop 0
	global_load_lds_dwordx4 v136, s[38:39]
	s_add_i32 m0, s42, 0x2000
	s_nop 0
	global_load_lds_dwordx4 v140, s[38:39]
	s_cmp_eq_u32 s27, 28
	s_cbranch_scc0 .Lq306_nl
	s_mov_b32 m0, s61
	s_nop 0
	global_load_lds_dwordx4 v14, s[100:101]
	s_mov_b32 m0, s64
	s_nop 0
	global_load_lds_dwordx4 v138, s[100:101]

.LBB0_1664:
	s_add_u32 s44, s42, 0xfff80080
	s_addc_u32 s45, s43, -1
	s_add_i32 s64, 0, 0x10000
	s_cmp_eq_u32 s61, 28
	s_cselect_b32 s47, s29, s45
	s_cselect_b32 s46, s53, s44
	v_add_u32_e32 v151, s64, v141
	s_cselect_b32 s45, s13, s60
	s_cselect_b32 s44, s54, s55
	s_add_i32 s67, 0, 0x14000
	ds_read_b128 v[162:165], v151
	ds_read_b128 v[166:169], v151 offset:1024
	ds_read_b128 v[170:173], v151 offset:2048
	ds_read_b128 v[174:177], v151 offset:3072
	v_add_u32_e32 v151, s67, v141
	ds_read_b128 v[184:187], v151
	ds_read_b128 v[188:191], v151 offset:1024
	ds_read_b128 v[192:195], v151 offset:2048
	ds_read_b128 v[196:199], v151 offset:3072
	s_cmp_lg_u32 s61, -2
	s_cbranch_scc0 .Lq1664_nf
	s_mov_b32 m0, s48
	s_nop 0
	global_load_lds_dwordx4 v138, s[100:101]
	s_mov_b32 m0, s49
	s_nop 0
	global_load_lds_dwordx4 v136, s[100:101]
.Lq1664_nf:
	s_add_i32 m0, s25, 0xc000
	ds_read_b128 v[200:203], v149
	ds_read_b128 v[214:217], v149 offset:1024
	ds_read_b128 v[218:221], v149 offset:2048
	ds_read_b128 v[222:225], v149 offset:3072
	ds_read_b128 v[226:229], v149 offset:4096
	ds_read_b128 v[230:233], v149 offset:5120
	ds_read_b128 v[234:237], v149 offset:6144
	ds_read_b128 v[238:241], v149 offset:7168
	global_load_lds_dwordx4 v142, s[42:43]
	s_add_i32 m0, s25, 0xe000
	s_nop 0
	global_load_lds_dwordx4 v144, s[42:43]
	s_waitcnt vmcnt(8)
	s_waitcnt lgkmcnt(0)
	s_barrier
	s_setprio 1
	s_waitcnt lgkmcnt(0)
	v_mfma_f32_16x16x32_bf16 v[132:135], v[162:165], v[200:203], v[132:135]
	v_mfma_f32_16x16x32_bf16 v[128:131], v[170:173], v[200:203], v[128:131]
	v_mfma_f32_16x16x32_bf16 v[116:119], v[162:165], v[218:221], v[116:119]
	v_mfma_f32_16x16x32_bf16 v[112:115], v[170:173], v[218:221], v[112:115]
	v_mfma_f32_16x16x32_bf16 v[100:103], v[162:165], v[226:229], v[100:103]
	v_mfma_f32_16x16x32_bf16 v[96:99], v[170:173], v[226:229], v[96:99]
	v_mfma_f32_16x16x32_bf16 v[84:87], v[162:165], v[234:237], v[84:87]
	v_mfma_f32_16x16x32_bf16 v[80:83], v[170:173], v[234:237], v[80:83]
	v_mfma_f32_16x16x32_bf16 v[132:135], v[166:169], v[214:217], v[132:135]
	v_mfma_f32_16x16x32_bf16 v[128:131], v[174:177], v[214:217], v[128:131]
	v_mfma_f32_16x16x32_bf16 v[116:119], v[166:169], v[222:225], v[116:119]
	v_mfma_f32_16x16x32_bf16 v[112:115], v[174:177], v[222:225], v[112:115]
	v_mfma_f32_16x16x32_bf16 v[100:103], v[166:169], v[230:233], v[100:103]
	v_mfma_f32_16x16x32_bf16 v[96:99], v[174:177], v[230:233], v[96:99]
	v_mfma_f32_16x16x32_bf16 v[84:87], v[166:169], v[238:241], v[84:87]
	v_mfma_f32_16x16x32_bf16 v[80:83], v[174:177], v[238:241], v[80:83]
	s_setprio 0
	s_setprio 1
	v_mfma_f32_16x16x32_bf16 v[124:127], v[184:187], v[200:203], v[124:127]
	v_mfma_f32_16x16x32_bf16 v[120:123], v[192:195], v[200:203], v[120:123]
	v_mfma_f32_16x16x32_bf16 v[108:111], v[184:187], v[218:221], v[108:111]
	v_mfma_f32_16x16x32_bf16 v[104:107], v[192:195], v[218:221], v[104:107]
	v_mfma_f32_16x16x32_bf16 v[92:95], v[184:187], v[226:229], v[92:95]
	v_mfma_f32_16x16x32_bf16 v[88:91], v[192:195], v[226:229], v[88:91]
	v_mfma_f32_16x16x32_bf16 v[76:79], v[184:187], v[234:237], v[76:79]
	v_mfma_f32_16x16x32_bf16 v[72:75], v[192:195], v[234:237], v[72:75]
	v_mfma_f32_16x16x32_bf16 v[124:127], v[188:191], v[214:217], v[124:127]
	v_mfma_f32_16x16x32_bf16 v[120:123], v[196:199], v[214:217], v[120:123]
	v_mfma_f32_16x16x32_bf16 v[108:111], v[188:191], v[222:225], v[108:111]
	v_mfma_f32_16x16x32_bf16 v[104:107], v[196:199], v[222:225], v[104:107]
	v_mfma_f32_16x16x32_bf16 v[92:95], v[188:191], v[230:233], v[92:95]
	v_mfma_f32_16x16x32_bf16 v[88:91], v[196:199], v[230:233], v[88:91]
	v_mfma_f32_16x16x32_bf16 v[76:79], v[188:191], v[238:241], v[76:79]
	v_mfma_f32_16x16x32_bf16 v[72:75], v[196:199], v[238:241], v[72:75]
	s_setprio 0
	s_barrier
	s_add_u32 s98, s44, s22
	s_addc_u32 s99, s45, s23
	s_add_u32 s100, s46, s22
	s_addc_u32 s101, s47, s23
	s_add_i32 s64, s64, s20
	s_mov_b32 m0, s64
	ds_read_b128 v[200:203], v149 offset:16384
	ds_read_b128 v[214:217], v149 offset:17408
	ds_read_b128 v[218:221], v149 offset:18432
	ds_read_b128 v[222:225], v149 offset:19456
	ds_read_b128 v[226:229], v149 offset:20480
	ds_read_b128 v[230:233], v149 offset:21504
	ds_read_b128 v[234:237], v149 offset:22528
	ds_read_b128 v[238:241], v149 offset:23552
	global_load_lds_dwordx4 v34, s[44:45]
	s_add_i32 m0, s64, 0x2000
	s_add_u32 s64, s44, 0x80000
	s_addc_u32 s65, s45, 0
	s_add_i32 s67, s67, s20
	global_load_lds_dwordx4 v14, s[44:45]
	s_mov_b32 m0, s67
	s_nop 0
	global_load_lds_dwordx4 v34, s[64:65]
	s_add_i32 m0, s67, 0x2000
	s_nop 0
	global_load_lds_dwordx4 v14, s[64:65]
	s_waitcnt vmcnt(6)
	s_waitcnt lgkmcnt(0)
	s_barrier
	s_setprio 1
	s_waitcnt lgkmcnt(0)
	v_mfma_f32_16x16x32_bf16 v[68:71], v[162:165], v[200:203], v[68:71]
	v_mfma_f32_16x16x32_bf16 v[64:67], v[170:173], v[200:203], v[64:67]
	v_mfma_f32_16x16x32_bf16 v[52:55], v[162:165], v[218:221], v[52:55]
	v_mfma_f32_16x16x32_bf16 v[48:51], v[170:173], v[218:221], v[48:51]
	v_mfma_f32_16x16x32_bf16 v[36:39], v[162:165], v[226:229], v[36:39]
	v_mfma_f32_16x16x32_bf16 v[30:33], v[170:173], v[226:229], v[30:33]
	v_mfma_f32_16x16x32_bf16 v[18:21], v[162:165], v[234:237], v[18:21]
	v_mfma_f32_16x16x32_bf16 v[10:13], v[170:173], v[234:237], v[10:13]
	v_mfma_f32_16x16x32_bf16 v[68:71], v[166:169], v[214:217], v[68:71]
	v_mfma_f32_16x16x32_bf16 v[64:67], v[174:177], v[214:217], v[64:67]
	v_mfma_f32_16x16x32_bf16 v[52:55], v[166:169], v[222:225], v[52:55]
	v_mfma_f32_16x16x32_bf16 v[48:51], v[174:177], v[222:225], v[48:51]
	v_mfma_f32_16x16x32_bf16 v[36:39], v[166:169], v[230:233], v[36:39]
	v_mfma_f32_16x16x32_bf16 v[30:33], v[174:177], v[230:233], v[30:33]
	v_mfma_f32_16x16x32_bf16 v[18:21], v[166:169], v[238:241], v[18:21]
	v_mfma_f32_16x16x32_bf16 v[10:13], v[174:177], v[238:241], v[10:13]
	s_setprio 0
	s_setprio 1
	v_mfma_f32_16x16x32_bf16 v[60:63], v[184:187], v[200:203], v[60:63]
	v_mfma_f32_16x16x32_bf16 v[56:59], v[192:195], v[200:203], v[56:59]
	v_mfma_f32_16x16x32_bf16 v[44:47], v[184:187], v[218:221], v[44:47]
	v_mfma_f32_16x16x32_bf16 v[40:43], v[192:195], v[218:221], v[40:43]
	v_mfma_f32_16x16x32_bf16 v[26:29], v[184:187], v[226:229], v[26:29]
	v_mfma_f32_16x16x32_bf16 v[22:25], v[192:195], v[226:229], v[22:25]
	v_mfma_f32_16x16x32_bf16 v[6:9], v[184:187], v[234:237], v[6:9]
	v_mfma_f32_16x16x32_bf16 v[2:5], v[192:195], v[234:237], v[2:5]
	v_mfma_f32_16x16x32_bf16 v[60:63], v[188:191], v[214:217], v[60:63]
	v_mfma_f32_16x16x32_bf16 v[56:59], v[196:199], v[214:217], v[56:59]
	v_mfma_f32_16x16x32_bf16 v[44:47], v[188:191], v[222:225], v[44:47]
	v_mfma_f32_16x16x32_bf16 v[40:43], v[196:199], v[222:225], v[40:43]
	v_mfma_f32_16x16x32_bf16 v[26:29], v[188:191], v[230:233], v[26:29]
	v_mfma_f32_16x16x32_bf16 v[22:25], v[196:199], v[230:233], v[22:25]
	v_mfma_f32_16x16x32_bf16 v[6:9], v[188:191], v[238:241], v[6:9]
	v_mfma_f32_16x16x32_bf16 v[2:5], v[196:199], v[238:241], v[2:5]
	s_setprio 0
	s_barrier
	s_mov_b32 m0, s25
	s_nop 0
	global_load_lds_dwordx4 v138, s[46:47]
	s_mov_b32 m0, s26
	s_nop 0
	global_load_lds_dwordx4 v136, s[46:47]
	s_add_i32 s64, 0, 0x18000
	v_add_u32_e32 v151, s64, v141
	s_add_i32 s65, 0, 0x1c000
	ds_read_b128 v[162:165], v151
	ds_read_b128 v[166:169], v151 offset:1024
	ds_read_b128 v[170:173], v151 offset:2048
	ds_read_b128 v[174:177], v151 offset:3072
	v_add_u32_e32 v151, s65, v141
	ds_read_b128 v[184:187], v151
	ds_read_b128 v[188:191], v151 offset:1024
	ds_read_b128 v[192:195], v151 offset:2048
	ds_read_b128 v[196:199], v151 offset:3072
	s_add_u32 s46, s46, 0x80000
	s_addc_u32 s47, s47, 0
	s_mov_b32 m0, s27
	ds_read_b128 v[200:203], v149 offset:32768
	ds_read_b128 v[214:217], v149 offset:33792
	ds_read_b128 v[218:221], v149 offset:34816
	ds_read_b128 v[222:225], v149 offset:35840
	ds_read_b128 v[226:229], v149 offset:36864
	ds_read_b128 v[230:233], v149 offset:37888
	ds_read_b128 v[234:237], v149 offset:38912
	ds_read_b128 v[238:241], v149 offset:39936
	global_load_lds_dwordx4 v138, s[46:47]
	s_mov_b32 m0, s31
	s_nop 0
	global_load_lds_dwordx4 v136, s[46:47]
	s_waitcnt vmcnt(8)
	s_waitcnt lgkmcnt(0)
	s_barrier
	s_setprio 1
	s_waitcnt lgkmcnt(0)
	v_mfma_f32_16x16x32_bf16 v[132:135], v[162:165], v[200:203], v[132:135]
	v_mfma_f32_16x16x32_bf16 v[128:131], v[170:173], v[200:203], v[128:131]
	v_mfma_f32_16x16x32_bf16 v[116:119], v[162:165], v[218:221], v[116:119]
	v_mfma_f32_16x16x32_bf16 v[112:115], v[170:173], v[218:221], v[112:115]
	v_mfma_f32_16x16x32_bf16 v[100:103], v[162:165], v[226:229], v[100:103]
	v_mfma_f32_16x16x32_bf16 v[96:99], v[170:173], v[226:229], v[96:99]
	v_mfma_f32_16x16x32_bf16 v[84:87], v[162:165], v[234:237], v[84:87]
	v_mfma_f32_16x16x32_bf16 v[80:83], v[170:173], v[234:237], v[80:83]
	v_mfma_f32_16x16x32_bf16 v[132:135], v[166:169], v[214:217], v[132:135]
	v_mfma_f32_16x16x32_bf16 v[128:131], v[174:177], v[214:217], v[128:131]
	v_mfma_f32_16x16x32_bf16 v[116:119], v[166:169], v[222:225], v[116:119]
	v_mfma_f32_16x16x32_bf16 v[112:115], v[174:177], v[222:225], v[112:115]
	v_mfma_f32_16x16x32_bf16 v[100:103], v[166:169], v[230:233], v[100:103]
	v_mfma_f32_16x16x32_bf16 v[96:99], v[174:177], v[230:233], v[96:99]
	v_mfma_f32_16x16x32_bf16 v[84:87], v[166:169], v[238:241], v[84:87]
	v_mfma_f32_16x16x32_bf16 v[80:83], v[174:177], v[238:241], v[80:83]
	s_setprio 0
	s_setprio 1
	v_mfma_f32_16x16x32_bf16 v[124:127], v[184:187], v[200:203], v[124:127]
	v_mfma_f32_16x16x32_bf16 v[120:123], v[192:195], v[200:203], v[120:123]
	v_mfma_f32_16x16x32_bf16 v[108:111], v[184:187], v[218:221], v[108:111]
	v_mfma_f32_16x16x32_bf16 v[104:107], v[192:195], v[218:221], v[104:107]
	v_mfma_f32_16x16x32_bf16 v[92:95], v[184:187], v[226:229], v[92:95]
	v_mfma_f32_16x16x32_bf16 v[88:91], v[192:195], v[226:229], v[88:91]
	v_mfma_f32_16x16x32_bf16 v[76:79], v[184:187], v[234:237], v[76:79]
	v_mfma_f32_16x16x32_bf16 v[72:75], v[192:195], v[234:237], v[72:75]
	v_mfma_f32_16x16x32_bf16 v[124:127], v[188:191], v[214:217], v[124:127]
	v_mfma_f32_16x16x32_bf16 v[120:123], v[196:199], v[214:217], v[120:123]
	v_mfma_f32_16x16x32_bf16 v[108:111], v[188:191], v[222:225], v[108:111]
	v_mfma_f32_16x16x32_bf16 v[104:107], v[196:199], v[222:225], v[104:107]
	v_mfma_f32_16x16x32_bf16 v[92:95], v[188:191], v[230:233], v[92:95]
	v_mfma_f32_16x16x32_bf16 v[88:91], v[196:199], v[230:233], v[88:91]
	v_mfma_f32_16x16x32_bf16 v[76:79], v[188:191], v[238:241], v[76:79]
	v_mfma_f32_16x16x32_bf16 v[72:75], v[196:199], v[238:241], v[72:75]
	s_setprio 0
	s_barrier
	s_add_i32 s46, s64, s20
	s_mov_b32 m0, s46
	ds_read_b128 v[200:203], v149 offset:49152
	ds_read_b128 v[214:217], v149 offset:50176
	ds_read_b128 v[218:221], v149 offset:51200
	ds_read_b128 v[222:225], v149 offset:52224
	ds_read_b128 v[226:229], v149 offset:53248
	ds_read_b128 v[230:233], v149 offset:54272
	ds_read_b128 v[234:237], v149 offset:55296
	ds_read_b128 v[238:241], v149 offset:56320
	global_load_lds_dwordx4 v34, s[98:99]
	s_add_i32 m0, s46, 0x2000
	s_add_u32 s44, s44, 0x80080
	s_addc_u32 s45, s45, 0
	s_add_i32 s46, s65, s20
	global_load_lds_dwordx4 v14, s[98:99]
	s_mov_b32 m0, s46
	s_nop 0
	global_load_lds_dwordx4 v34, s[44:45]
	s_add_i32 m0, s46, 0x2000
	s_nop 0
	global_load_lds_dwordx4 v14, s[44:45]
	s_cmp_eq_u32 s61, 28
	s_cbranch_scc0 .Lq1664_nl
	s_mov_b32 m0, s48
	s_nop 0
	global_load_lds_dwordx4 v138, s[100:101]
	s_mov_b32 m0, s49
	s_nop 0
	global_load_lds_dwordx4 v136, s[100:101]
